# in-projection sample-row epilogue: xor-1/2/4/8 lane exchanges of the row sums (RMSNorm / QK-norm) done with DPP moves instead of ds_bpermute round trips (bit-identical sums)
# baseline (speedup 1.0000x reference)
;     ...
;         if (AF32) {
; #pragma unroll
;             for (int i = 0; i < 8; ++i) { float q = q8[i]; q += __shfl_xor(q, 1); q += __shfl_xor(q, 2); q += __shfl_xor(q, 4); q += __shfl_xor(q, 8);
;                 if ((lane & 15) == 0) SSP[wave * 32 + 4 * i + (lane >> 4)] = q; }
;         }
.LBB0_263:
	v_and_b32_e32 v3, 64, v205
	v_xor_b32_e32 v0, 1, v205
	v_add_u32_e32 v68, 64, v3
	v_cmp_lt_i32_e32 vcc, v0, v68
	v_xor_b32_e32 v3, 2, v205
	v_xor_b32_e32 v19, 4, v205
	v_cndmask_b32_e32 v0, v205, v0, vcc
	v_lshlrev_b32_e32 v69, 2, v0
	s_nop 1
	v_mov_b32_dpp v0, v40 quad_perm:[1,0,3,2] row_mask:0xf bank_mask:0xf
	v_cmp_lt_i32_e32 vcc, v3, v68
	s_waitcnt lgkmcnt(0)
	v_add_f32_e32 v0, v40, v0
	v_cndmask_b32_e32 v3, v205, v3, vcc
	v_lshlrev_b32_e32 v70, 2, v3
	s_nop 1
	v_mov_b32_dpp v3, v0 quad_perm:[2,3,0,1] row_mask:0xf bank_mask:0xf
	v_cmp_lt_i32_e32 vcc, v19, v68
	s_waitcnt lgkmcnt(0)
	v_add_f32_e32 v0, v0, v3
	v_cndmask_b32_e32 v19, v205, v19, vcc
	v_lshlrev_b32_e32 v71, 2, v19
	s_nop 1
	v_mov_b32_dpp v3, v0 row_half_mirror row_mask:0xf bank_mask:0xf
	v_xor_b32_e32 v19, 8, v205
	v_cmp_lt_i32_e32 vcc, v19, v68
	s_waitcnt lgkmcnt(0)
	v_add_f32_e32 v0, v0, v3
	v_cndmask_b32_e32 v19, v205, v19, vcc
	v_lshlrev_b32_e32 v72, 2, v19
	s_nop 1
	v_mov_b32_dpp v3, v0 row_mirror row_mask:0xf bank_mask:0xf
	s_and_saveexec_b64 s[12:13], s[4:5]
	s_cbranch_execz .LBB0_265
	s_waitcnt lgkmcnt(0)
	v_add_f32_e32 v0, v0, v3
	ds_write_b32 v133, v0
.LBB0_265:
	s_or_b64 exec, exec, s[12:13]
	s_nop 1
	v_mov_b32_dpp v0, v41 quad_perm:[1,0,3,2] row_mask:0xf bank_mask:0xf
	s_waitcnt lgkmcnt(0)
	v_add_f32_e32 v0, v41, v0
	s_nop 1
	v_mov_b32_dpp v3, v0 quad_perm:[2,3,0,1] row_mask:0xf bank_mask:0xf
	s_waitcnt lgkmcnt(0)
	v_add_f32_e32 v0, v0, v3
	s_nop 1
	v_mov_b32_dpp v3, v0 row_half_mirror row_mask:0xf bank_mask:0xf
	s_waitcnt lgkmcnt(0)
	v_add_f32_e32 v0, v0, v3
	s_nop 1
	v_mov_b32_dpp v3, v0 row_mirror row_mask:0xf bank_mask:0xf
	s_and_saveexec_b64 s[12:13], s[4:5]
	s_cbranch_execz .LBB0_267
	s_waitcnt lgkmcnt(0)
	v_add_f32_e32 v0, v0, v3
	ds_write_b32 v133, v0 offset:16
.LBB0_267:
	s_or_b64 exec, exec, s[12:13]
	s_nop 1
	v_mov_b32_dpp v0, v44 quad_perm:[1,0,3,2] row_mask:0xf bank_mask:0xf
	s_waitcnt lgkmcnt(0)
	v_add_f32_e32 v0, v44, v0
	s_nop 1
	v_mov_b32_dpp v3, v0 quad_perm:[2,3,0,1] row_mask:0xf bank_mask:0xf
	s_waitcnt lgkmcnt(0)
	v_add_f32_e32 v0, v0, v3
	s_nop 1
	v_mov_b32_dpp v3, v0 row_half_mirror row_mask:0xf bank_mask:0xf
	s_waitcnt lgkmcnt(0)
	v_add_f32_e32 v0, v0, v3
	s_nop 1
	v_mov_b32_dpp v3, v0 row_mirror row_mask:0xf bank_mask:0xf
	s_and_saveexec_b64 s[12:13], s[4:5]
	s_cbranch_execz .LBB0_269
	s_waitcnt lgkmcnt(0)
	v_add_f32_e32 v0, v0, v3
	ds_write_b32 v133, v0 offset:32
.LBB0_269:
	s_or_b64 exec, exec, s[12:13]
	s_nop 1
	v_mov_b32_dpp v0, v45 quad_perm:[1,0,3,2] row_mask:0xf bank_mask:0xf
	s_waitcnt lgkmcnt(0)
	v_add_f32_e32 v0, v45, v0
	s_nop 1
	v_mov_b32_dpp v3, v0 quad_perm:[2,3,0,1] row_mask:0xf bank_mask:0xf
	s_waitcnt lgkmcnt(0)
	v_add_f32_e32 v0, v0, v3
	s_nop 1
	v_mov_b32_dpp v3, v0 row_half_mirror row_mask:0xf bank_mask:0xf
	s_waitcnt lgkmcnt(0)
	v_add_f32_e32 v0, v0, v3
	s_nop 1
	v_mov_b32_dpp v3, v0 row_mirror row_mask:0xf bank_mask:0xf
	s_and_saveexec_b64 s[12:13], s[4:5]
	s_cbranch_execz .LBB0_271
	s_waitcnt lgkmcnt(0)
	v_add_f32_e32 v0, v0, v3
	ds_write_b32 v133, v0 offset:48
.LBB0_271:
	s_or_b64 exec, exec, s[12:13]
	s_nop 1
	v_mov_b32_dpp v0, v50 quad_perm:[1,0,3,2] row_mask:0xf bank_mask:0xf
	s_waitcnt lgkmcnt(0)
	v_add_f32_e32 v0, v50, v0
	s_nop 1
	v_mov_b32_dpp v3, v0 quad_perm:[2,3,0,1] row_mask:0xf bank_mask:0xf
	s_waitcnt lgkmcnt(0)
	v_add_f32_e32 v0, v0, v3
	s_nop 1
	v_mov_b32_dpp v3, v0 row_half_mirror row_mask:0xf bank_mask:0xf
	s_waitcnt lgkmcnt(0)
	v_add_f32_e32 v0, v0, v3
	s_nop 1
	v_mov_b32_dpp v3, v0 row_mirror row_mask:0xf bank_mask:0xf
	s_and_saveexec_b64 s[12:13], s[4:5]
	s_cbranch_execz .LBB0_273
	s_waitcnt lgkmcnt(0)
	v_add_f32_e32 v0, v0, v3
	ds_write_b32 v133, v0 offset:64
.LBB0_273:
	s_or_b64 exec, exec, s[12:13]
	s_nop 1
	v_mov_b32_dpp v0, v51 quad_perm:[1,0,3,2] row_mask:0xf bank_mask:0xf
	s_waitcnt lgkmcnt(0)
	v_add_f32_e32 v0, v51, v0
	s_nop 1
	v_mov_b32_dpp v3, v0 quad_perm:[2,3,0,1] row_mask:0xf bank_mask:0xf
	s_waitcnt lgkmcnt(0)
	v_add_f32_e32 v0, v0, v3
	s_nop 1
	v_mov_b32_dpp v3, v0 row_half_mirror row_mask:0xf bank_mask:0xf
	s_waitcnt lgkmcnt(0)
	v_add_f32_e32 v0, v0, v3
	s_nop 1
	v_mov_b32_dpp v3, v0 row_mirror row_mask:0xf bank_mask:0xf
	s_and_saveexec_b64 s[12:13], s[4:5]
	s_cbranch_execz .LBB0_275
	s_waitcnt lgkmcnt(0)
	v_add_f32_e32 v0, v0, v3
	ds_write_b32 v133, v0 offset:80
.LBB0_275:
	s_or_b64 exec, exec, s[12:13]
	s_nop 1
	v_mov_b32_dpp v0, v58 quad_perm:[1,0,3,2] row_mask:0xf bank_mask:0xf
	s_waitcnt lgkmcnt(0)
	v_add_f32_e32 v0, v58, v0
	s_nop 1
	v_mov_b32_dpp v3, v0 quad_perm:[2,3,0,1] row_mask:0xf bank_mask:0xf
	s_waitcnt lgkmcnt(0)
	v_add_f32_e32 v0, v0, v3
	s_nop 1
	v_mov_b32_dpp v3, v0 row_half_mirror row_mask:0xf bank_mask:0xf
	s_waitcnt lgkmcnt(0)
	v_add_f32_e32 v0, v0, v3
	s_nop 1
	v_mov_b32_dpp v3, v0 row_mirror row_mask:0xf bank_mask:0xf
	s_and_saveexec_b64 s[12:13], s[4:5]
	s_cbranch_execz .LBB0_277
	s_waitcnt lgkmcnt(0)
	v_add_f32_e32 v0, v0, v3
	ds_write_b32 v133, v0 offset:96
.LBB0_277:
	s_or_b64 exec, exec, s[12:13]
	s_nop 1
	v_mov_b32_dpp v0, v59 quad_perm:[1,0,3,2] row_mask:0xf bank_mask:0xf
	s_waitcnt lgkmcnt(0)
	v_add_f32_e32 v0, v59, v0
	s_nop 1
	v_mov_b32_dpp v3, v0 quad_perm:[2,3,0,1] row_mask:0xf bank_mask:0xf
	s_waitcnt lgkmcnt(0)
	v_add_f32_e32 v0, v0, v3
	s_nop 1
	v_mov_b32_dpp v3, v0 row_half_mirror row_mask:0xf bank_mask:0xf
	s_waitcnt lgkmcnt(0)
	v_add_f32_e32 v0, v0, v3
	s_nop 1
	v_mov_b32_dpp v3, v0 row_mirror row_mask:0xf bank_mask:0xf
	s_and_saveexec_b64 s[12:13], s[4:5]
	s_cbranch_execz .LBB0_279
	s_waitcnt lgkmcnt(0)
	v_add_f32_e32 v0, v0, v3
	ds_write_b32 v133, v0 offset:112

; __device__ __forceinline__ unsigned f2bf(float f) { unsigned u = __builtin_bit_cast(unsigned, f); return (u + 0x7fffu + ((u >> 16) & 1u)) >> 16; }
;     __device__ __forceinline__ void operator()(const f32x16& acc0, const f32x16& acc1, int rb, int cg, int r32, int hi, const float (&ss)[16]) const {
;     ...
;             } else if (pn < 10) {
;                 float q = v0 * v0 + v1 * v1;
;                 q += __shfl_xor(q, 1); q += __shfl_xor(q, 2); q += __shfl_xor(q, 4); q += __shfl_xor(q, 8); q += __shfl_xor(q, 16);
;                 const float rn = rsqrtf(q * (1.0f / 64.0f) + EPS);
;                 const bool isq = pn < 8;
;                 const float* gp = isq ? qg : kg;
;                 const int col = ((pn & 1) * 4 + hd) * 64 + r32;
;                 const float a0 = v0 * rn * gp[r32], a1 = v1 * rn * gp[32 + r32];
;                 if (isq) { bf16_t* SQ = (bf16_t*)(ws + WS_SQ); SQ[(size_t)row * 512 + col] = (bf16_t)f2bf(a0 * QSCALE); SQ[(size_t)row * 512 + col + 32] = (bf16_t)f2bf(a1 * QSCALE); }
;                 else { bf16_t* KB = (bf16_t*)(ws + WS_KB); KB[(size_t)row * 512 + col] = (bf16_t)f2bf(a0); KB[(size_t)row * 512 + col + 32] = (bf16_t)f2bf(a1);
;                     Ks[(size_t)rs_ * 512 + col] = a0; Ks[(size_t)rs_ * 512 + col + 32] = a1; }
.LBB0_284:
	s_andn2_b64 vcc, exec, s[10:11]
	s_cbranch_vccnz .LBB0_289
	s_and_b64 s[10:11], s[44:45], exec
	s_cselect_b32 s11, s62, s64
	s_cselect_b32 s10, s61, s63
	v_lshlrev_b32_e32 v0, 2, v98
	global_load_dword v51, v0, s[10:11]
	s_nop 0
	global_load_dword v0, v0, s[10:11] offset:128
	v_pk_mul_f32 v[66:67], v[62:63], v[62:63]
	s_and_b64 s[10:11], exec, s[42:43]
	v_add_f32_e32 v61, v66, v67
	s_nop 1
	v_mov_b32_dpp v66, v61 quad_perm:[1,0,3,2] row_mask:0xf bank_mask:0xf
	v_xor_b32_e32 v67, 16, v205
	v_cmp_lt_i32_e32 vcc, v67, v68
	s_mov_b64 s[46:47], -1
	s_waitcnt lgkmcnt(0)
	v_add_f32_e32 v61, v61, v66
	s_nop 1
	v_mov_b32_dpp v66, v61 quad_perm:[2,3,0,1] row_mask:0xf bank_mask:0xf
	v_cndmask_b32_e32 v67, v205, v67, vcc
	v_lshlrev_b32_e32 v67, 2, v67
	s_waitcnt lgkmcnt(0)
	v_add_f32_e32 v61, v61, v66
	s_nop 1
	v_mov_b32_dpp v66, v61 row_half_mirror row_mask:0xf bank_mask:0xf
	s_waitcnt lgkmcnt(0)
	v_add_f32_e32 v61, v61, v66
	s_nop 1
	v_mov_b32_dpp v66, v61 row_mirror row_mask:0xf bank_mask:0xf
	s_waitcnt lgkmcnt(0)
	v_add_f32_e32 v61, v61, v66
	ds_bpermute_b32 v66, v67, v61
	s_waitcnt lgkmcnt(0)
	v_add_f32_e32 v61, v61, v66
	v_fmamk_f32 v61, v61, 0x3c800000, v201
	v_mul_f32_e32 v66, 0x4b800000, v61
	v_cmp_gt_f32_e32 vcc, s3, v61
	s_nop 1
	v_cndmask_b32_e32 v61, v61, v66, vcc
	v_rsq_f32_e32 v61, v61
	s_nop 0
	v_mul_f32_e32 v66, 0x45800000, v61
	v_cndmask_b32_e32 v61, v61, v66, vcc
	v_mul_f32_e32 v66, v62, v61
	v_mul_f32_e32 v61, v63, v61
	s_mov_b64 vcc, s[10:11]
	s_waitcnt vmcnt(1)
	v_mul_f32_e32 v51, v51, v66
	s_waitcnt vmcnt(0)
	v_mul_f32_e32 v0, v0, v61
	s_cbranch_vccz .LBB0_287
	v_bfe_u32 v61, v51, 16, 1
	v_lshlrev_b64 v[66:67], 10, v[64:65]
	v_add3_u32 v61, v51, v61, s2
	v_lshl_add_u64 v[66:67], v[54:55], 0, v[66:67]
	global_store_short_d16_hi v[66:67], v61, off
	v_bfe_u32 v61, v0, 16, 1
	v_add3_u32 v61, v0, v61, s2
	global_store_short_d16_hi v[66:67], v61, off offset:64
	v_ashrrev_i32_e32 v61, 31, v60
	v_lshlrev_b64 v[66:67], 11, v[60:61]
	v_lshl_add_u64 v[66:67], v[52:53], 0, v[66:67]
	global_store_dword v[66:67], v51, off
	global_store_dword v[66:67], v0, off offset:128
	s_mov_b64 s[46:47], 0

; __device__ __forceinline__ unsigned f2bf(float f) { unsigned u = __builtin_bit_cast(unsigned, f); return (u + 0x7fffu + ((u >> 16) & 1u)) >> 16; }
;     __device__ __forceinline__ void operator()(const f32x16& acc0, const f32x16& acc1, int rb, int cg, int r32, int hi, const float (&ss)[16]) const {
;     ...
;             } else if (pn < 10) {
;                 float q = v0 * v0 + v1 * v1;
;                 q += __shfl_xor(q, 1); q += __shfl_xor(q, 2); q += __shfl_xor(q, 4); q += __shfl_xor(q, 8); q += __shfl_xor(q, 16);
;                 const float rn = rsqrtf(q * (1.0f / 64.0f) + EPS);
;                 const bool isq = pn < 8;
;                 const float* gp = isq ? qg : kg;
;                 const int col = ((pn & 1) * 4 + hd) * 64 + r32;
;                 const float a0 = v0 * rn * gp[r32], a1 = v1 * rn * gp[32 + r32];
;                 if (isq) { bf16_t* SQ = (bf16_t*)(ws + WS_SQ); SQ[(size_t)row * 512 + col] = (bf16_t)f2bf(a0 * QSCALE); SQ[(size_t)row * 512 + col + 32] = (bf16_t)f2bf(a1 * QSCALE); }
;                 else { bf16_t* KB = (bf16_t*)(ws + WS_KB); KB[(size_t)row * 512 + col] = (bf16_t)f2bf(a0); KB[(size_t)row * 512 + col + 32] = (bf16_t)f2bf(a1);
;                     Ks[(size_t)rs_ * 512 + col] = a0; Ks[(size_t)rs_ * 512 + col + 32] = a1; }
.LBB0_300:
	s_andn2_b64 vcc, exec, s[16:17]
	s_cbranch_vccnz .LBB0_305
	s_and_b64 s[16:17], s[44:45], exec
	s_cselect_b32 s17, s62, s64
	s_cselect_b32 s16, s61, s63
	v_lshlrev_b32_e32 v0, 2, v98
	global_load_dword v41, v0, s[16:17]
	s_nop 0
	global_load_dword v0, v0, s[16:17] offset:128
	v_pk_mul_f32 v[74:75], v[62:63], v[62:63]
	v_xor_b32_e32 v67, 16, v205
	v_add_f32_e32 v51, v74, v75
	s_nop 1
	v_mov_b32_dpp v61, v51 quad_perm:[1,0,3,2] row_mask:0xf bank_mask:0xf
	v_cmp_lt_i32_e32 vcc, v67, v68
	s_waitcnt lgkmcnt(0)
	v_add_f32_e32 v51, v51, v61
	s_nop 1
	v_mov_b32_dpp v61, v51 quad_perm:[2,3,0,1] row_mask:0xf bank_mask:0xf
	v_cndmask_b32_e32 v67, v205, v67, vcc
	v_lshlrev_b32_e32 v67, 2, v67
	s_andn2_b64 vcc, exec, s[42:43]
	s_waitcnt lgkmcnt(0)
	v_add_f32_e32 v51, v51, v61
	s_nop 1
	v_mov_b32_dpp v61, v51 row_half_mirror row_mask:0xf bank_mask:0xf
	s_waitcnt lgkmcnt(0)
	v_add_f32_e32 v51, v51, v61
	s_nop 1
	v_mov_b32_dpp v61, v51 row_mirror row_mask:0xf bank_mask:0xf
	s_waitcnt lgkmcnt(0)
	v_add_f32_e32 v51, v51, v61
	ds_bpermute_b32 v61, v67, v51
	s_waitcnt lgkmcnt(0)
	v_add_f32_e32 v51, v51, v61
	v_fmamk_f32 v51, v51, 0x3c800000, v201
	v_mul_f32_e32 v61, 0x4b800000, v51
	v_cmp_gt_f32_e64 s[16:17], s3, v51
	s_nop 1
	v_cndmask_b32_e64 v51, v51, v61, s[16:17]
	v_rsq_f32_e32 v51, v51
	s_nop 0
	v_mul_f32_e32 v61, 0x45800000, v51
	v_cndmask_b32_e64 v51, v51, v61, s[16:17]
	v_mul_f32_e32 v61, v62, v51
	v_mul_f32_e32 v51, v63, v51
	s_mov_b64 s[16:17], -1
	s_waitcnt vmcnt(1)
	v_mul_f32_e32 v41, v41, v61
	s_waitcnt vmcnt(0)
	v_mul_f32_e32 v0, v0, v51
	s_cbranch_vccnz .LBB0_303
	v_bfe_u32 v51, v41, 16, 1
	v_lshlrev_b64 v[74:75], 10, v[64:65]
	v_add3_u32 v51, v41, v51, s2
	v_lshl_add_u64 v[74:75], v[54:55], 0, v[74:75]
	v_ashrrev_i32_e32 v67, 31, v66
	global_store_short_d16_hi v[74:75], v51, off
	v_bfe_u32 v51, v0, 16, 1
	v_lshlrev_b64 v[66:67], 11, v[66:67]
	v_add3_u32 v51, v0, v51, s2
	v_lshl_add_u64 v[66:67], v[52:53], 0, v[66:67]
	s_mov_b64 s[16:17], 0
	global_store_short_d16_hi v[74:75], v51, off offset:64
	global_store_dword v[66:67], v41, off
	global_store_dword v[66:67], v0, off offset:128

; __device__ __forceinline__ unsigned f2bf(float f) { unsigned u = __builtin_bit_cast(unsigned, f); return (u + 0x7fffu + ((u >> 16) & 1u)) >> 16; }
;     __device__ __forceinline__ void operator()(const f32x16& acc0, const f32x16& acc1, int rb, int cg, int r32, int hi, const float (&ss)[16]) const {
;     ...
;             } else if (pn < 10) {
;                 float q = v0 * v0 + v1 * v1;
;                 q += __shfl_xor(q, 1); q += __shfl_xor(q, 2); q += __shfl_xor(q, 4); q += __shfl_xor(q, 8); q += __shfl_xor(q, 16);
;                 const float rn = rsqrtf(q * (1.0f / 64.0f) + EPS);
;                 const bool isq = pn < 8;
;                 const float* gp = isq ? qg : kg;
;                 const int col = ((pn & 1) * 4 + hd) * 64 + r32;
;                 const float a0 = v0 * rn * gp[r32], a1 = v1 * rn * gp[32 + r32];
;                 if (isq) { bf16_t* SQ = (bf16_t*)(ws + WS_SQ); SQ[(size_t)row * 512 + col] = (bf16_t)f2bf(a0 * QSCALE); SQ[(size_t)row * 512 + col + 32] = (bf16_t)f2bf(a1 * QSCALE); }
;                 else { bf16_t* KB = (bf16_t*)(ws + WS_KB); KB[(size_t)row * 512 + col] = (bf16_t)f2bf(a0); KB[(size_t)row * 512 + col + 32] = (bf16_t)f2bf(a1);
;                     Ks[(size_t)rs_ * 512 + col] = a0; Ks[(size_t)rs_ * 512 + col + 32] = a1; }
.LBB0_316:
	s_andn2_b64 vcc, exec, s[16:17]
	s_cbranch_vccnz .LBB0_321
	s_and_b64 s[16:17], s[44:45], exec
	s_cselect_b32 s17, s62, s64
	s_cselect_b32 s16, s61, s63
	v_lshlrev_b32_e32 v0, 2, v98
	global_load_dword v41, v0, s[16:17]
	s_nop 0
	global_load_dword v0, v0, s[16:17] offset:128
	v_pk_mul_f32 v[74:75], v[62:63], v[62:63]
	v_xor_b32_e32 v61, 16, v205
	v_add_f32_e32 v47, v74, v75
	s_nop 1
	v_mov_b32_dpp v51, v47 quad_perm:[1,0,3,2] row_mask:0xf bank_mask:0xf
	v_cmp_lt_i32_e32 vcc, v61, v68
	s_waitcnt lgkmcnt(0)
	v_add_f32_e32 v47, v47, v51
	s_nop 1
	v_mov_b32_dpp v51, v47 quad_perm:[2,3,0,1] row_mask:0xf bank_mask:0xf
	v_cndmask_b32_e32 v61, v205, v61, vcc
	v_lshlrev_b32_e32 v61, 2, v61
	s_andn2_b64 vcc, exec, s[42:43]
	s_waitcnt lgkmcnt(0)
	v_add_f32_e32 v47, v47, v51
	s_nop 1
	v_mov_b32_dpp v51, v47 row_half_mirror row_mask:0xf bank_mask:0xf
	s_waitcnt lgkmcnt(0)
	v_add_f32_e32 v47, v47, v51
	s_nop 1
	v_mov_b32_dpp v51, v47 row_mirror row_mask:0xf bank_mask:0xf
	s_waitcnt lgkmcnt(0)
	v_add_f32_e32 v47, v47, v51
	ds_bpermute_b32 v51, v61, v47
	s_waitcnt lgkmcnt(0)
	v_add_f32_e32 v47, v47, v51
	v_fmamk_f32 v47, v47, 0x3c800000, v201
	v_mul_f32_e32 v51, 0x4b800000, v47
	v_cmp_gt_f32_e64 s[16:17], s3, v47
	s_nop 1
	v_cndmask_b32_e64 v47, v47, v51, s[16:17]
	v_rsq_f32_e32 v47, v47
	s_nop 0
	v_mul_f32_e32 v51, 0x45800000, v47
	v_cndmask_b32_e64 v47, v47, v51, s[16:17]
	v_mul_f32_e32 v51, v62, v47
	v_mul_f32_e32 v47, v63, v47
	s_mov_b64 s[16:17], -1
	s_waitcnt vmcnt(1)
	v_mul_f32_e32 v41, v41, v51
	s_waitcnt vmcnt(0)
	v_mul_f32_e32 v0, v0, v47
	s_cbranch_vccnz .LBB0_319
	v_bfe_u32 v47, v41, 16, 1
	v_lshlrev_b64 v[74:75], 10, v[64:65]
	v_add3_u32 v47, v41, v47, s2
	v_lshl_add_u64 v[74:75], v[54:55], 0, v[74:75]
	v_ashrrev_i32_e32 v67, 31, v66
	global_store_short_d16_hi v[74:75], v47, off
	v_bfe_u32 v47, v0, 16, 1
	v_lshlrev_b64 v[66:67], 11, v[66:67]
	v_add3_u32 v47, v0, v47, s2
	v_lshl_add_u64 v[66:67], v[52:53], 0, v[66:67]
	s_mov_b64 s[16:17], 0
	global_store_short_d16_hi v[74:75], v47, off offset:64
	global_store_dword v[66:67], v41, off
	global_store_dword v[66:67], v0, off offset:128

; __device__ __forceinline__ unsigned f2bf(float f) { unsigned u = __builtin_bit_cast(unsigned, f); return (u + 0x7fffu + ((u >> 16) & 1u)) >> 16; }
;     __device__ __forceinline__ void operator()(const f32x16& acc0, const f32x16& acc1, int rb, int cg, int r32, int hi, const float (&ss)[16]) const {
;     ...
;             } else if (pn < 10) {
;                 float q = v0 * v0 + v1 * v1;
;                 q += __shfl_xor(q, 1); q += __shfl_xor(q, 2); q += __shfl_xor(q, 4); q += __shfl_xor(q, 8); q += __shfl_xor(q, 16);
;                 const float rn = rsqrtf(q * (1.0f / 64.0f) + EPS);
;                 const bool isq = pn < 8;
;                 const float* gp = isq ? qg : kg;
;                 const int col = ((pn & 1) * 4 + hd) * 64 + r32;
;                 const float a0 = v0 * rn * gp[r32], a1 = v1 * rn * gp[32 + r32];
;                 if (isq) { bf16_t* SQ = (bf16_t*)(ws + WS_SQ); SQ[(size_t)row * 512 + col] = (bf16_t)f2bf(a0 * QSCALE); SQ[(size_t)row * 512 + col + 32] = (bf16_t)f2bf(a1 * QSCALE); }
;                 else { bf16_t* KB = (bf16_t*)(ws + WS_KB); KB[(size_t)row * 512 + col] = (bf16_t)f2bf(a0); KB[(size_t)row * 512 + col + 32] = (bf16_t)f2bf(a1);
;                     Ks[(size_t)rs_ * 512 + col] = a0; Ks[(size_t)rs_ * 512 + col + 32] = a1; }
.LBB0_332:
	s_andn2_b64 vcc, exec, s[16:17]
	s_cbranch_vccnz .LBB0_337
	s_and_b64 s[16:17], s[44:45], exec
	s_cselect_b32 s17, s62, s64
	s_cselect_b32 s16, s61, s63
	v_lshlrev_b32_e32 v0, 2, v98
	global_load_dword v39, v0, s[16:17]
	s_nop 0
	global_load_dword v0, v0, s[16:17] offset:128
	v_pk_mul_f32 v[74:75], v[62:63], v[62:63]
	v_xor_b32_e32 v51, 16, v205
	v_add_f32_e32 v41, v74, v75
	s_nop 1
	v_mov_b32_dpp v47, v41 quad_perm:[1,0,3,2] row_mask:0xf bank_mask:0xf
	v_cmp_lt_i32_e32 vcc, v51, v68
	s_waitcnt lgkmcnt(0)
	v_add_f32_e32 v41, v41, v47
	s_nop 1
	v_mov_b32_dpp v47, v41 quad_perm:[2,3,0,1] row_mask:0xf bank_mask:0xf
	v_cndmask_b32_e32 v51, v205, v51, vcc
	v_lshlrev_b32_e32 v51, 2, v51
	s_andn2_b64 vcc, exec, s[42:43]
	s_waitcnt lgkmcnt(0)
	v_add_f32_e32 v41, v41, v47
	s_nop 1
	v_mov_b32_dpp v47, v41 row_half_mirror row_mask:0xf bank_mask:0xf
	s_waitcnt lgkmcnt(0)
	v_add_f32_e32 v41, v41, v47
	s_nop 1
	v_mov_b32_dpp v47, v41 row_mirror row_mask:0xf bank_mask:0xf
	s_waitcnt lgkmcnt(0)
	v_add_f32_e32 v41, v41, v47
	ds_bpermute_b32 v47, v51, v41
	s_waitcnt lgkmcnt(0)
	v_add_f32_e32 v41, v41, v47
	v_fmamk_f32 v41, v41, 0x3c800000, v201
	v_mul_f32_e32 v47, 0x4b800000, v41
	v_cmp_gt_f32_e64 s[16:17], s3, v41
	s_nop 1
	v_cndmask_b32_e64 v41, v41, v47, s[16:17]
	v_rsq_f32_e32 v41, v41
	s_nop 0
	v_mul_f32_e32 v47, 0x45800000, v41
	v_cndmask_b32_e64 v41, v41, v47, s[16:17]
	v_mul_f32_e32 v47, v62, v41
	v_mul_f32_e32 v41, v63, v41
	s_mov_b64 s[16:17], -1
	s_waitcnt vmcnt(1)
	v_mul_f32_e32 v39, v39, v47
	s_waitcnt vmcnt(0)
	v_mul_f32_e32 v0, v0, v41
	s_cbranch_vccnz .LBB0_335
	v_bfe_u32 v41, v39, 16, 1
	v_lshlrev_b64 v[74:75], 10, v[64:65]
	v_add3_u32 v41, v39, v41, s2
	v_lshl_add_u64 v[74:75], v[54:55], 0, v[74:75]
	v_ashrrev_i32_e32 v67, 31, v66
	global_store_short_d16_hi v[74:75], v41, off
	v_bfe_u32 v41, v0, 16, 1
	v_lshlrev_b64 v[66:67], 11, v[66:67]
	v_add3_u32 v41, v0, v41, s2
	v_lshl_add_u64 v[66:67], v[52:53], 0, v[66:67]
	s_mov_b64 s[16:17], 0
	global_store_short_d16_hi v[74:75], v41, off offset:64
	global_store_dword v[66:67], v39, off
	global_store_dword v[66:67], v0, off offset:128

; __device__ __forceinline__ unsigned f2bf(float f) { unsigned u = __builtin_bit_cast(unsigned, f); return (u + 0x7fffu + ((u >> 16) & 1u)) >> 16; }
;     __device__ __forceinline__ void operator()(const f32x16& acc0, const f32x16& acc1, int rb, int cg, int r32, int hi, const float (&ss)[16]) const {
;     ...
;             } else if (pn < 10) {
;                 float q = v0 * v0 + v1 * v1;
;                 q += __shfl_xor(q, 1); q += __shfl_xor(q, 2); q += __shfl_xor(q, 4); q += __shfl_xor(q, 8); q += __shfl_xor(q, 16);
;                 const float rn = rsqrtf(q * (1.0f / 64.0f) + EPS);
;                 const bool isq = pn < 8;
;                 const float* gp = isq ? qg : kg;
;                 const int col = ((pn & 1) * 4 + hd) * 64 + r32;
;                 const float a0 = v0 * rn * gp[r32], a1 = v1 * rn * gp[32 + r32];
;                 if (isq) { bf16_t* SQ = (bf16_t*)(ws + WS_SQ); SQ[(size_t)row * 512 + col] = (bf16_t)f2bf(a0 * QSCALE); SQ[(size_t)row * 512 + col + 32] = (bf16_t)f2bf(a1 * QSCALE); }
;                 else { bf16_t* KB = (bf16_t*)(ws + WS_KB); KB[(size_t)row * 512 + col] = (bf16_t)f2bf(a0); KB[(size_t)row * 512 + col + 32] = (bf16_t)f2bf(a1);
;                     Ks[(size_t)rs_ * 512 + col] = a0; Ks[(size_t)rs_ * 512 + col + 32] = a1; }
.LBB0_348:
	s_andn2_b64 vcc, exec, s[16:17]
	s_cbranch_vccnz .LBB0_353
	s_and_b64 s[16:17], s[44:45], exec
	s_cselect_b32 s17, s62, s64
	s_cselect_b32 s16, s61, s63
	v_lshlrev_b32_e32 v0, 2, v98
	global_load_dword v39, v0, s[16:17]
	s_nop 0
	global_load_dword v0, v0, s[16:17] offset:128
	v_pk_mul_f32 v[74:75], v[62:63], v[62:63]
	v_xor_b32_e32 v49, 16, v205
	v_add_f32_e32 v41, v74, v75
	s_nop 1
	v_mov_b32_dpp v47, v41 quad_perm:[1,0,3,2] row_mask:0xf bank_mask:0xf
	v_cmp_lt_i32_e32 vcc, v49, v68
	s_waitcnt lgkmcnt(0)
	v_add_f32_e32 v41, v41, v47
	s_nop 1
	v_mov_b32_dpp v47, v41 quad_perm:[2,3,0,1] row_mask:0xf bank_mask:0xf
	v_cndmask_b32_e32 v49, v205, v49, vcc
	v_lshlrev_b32_e32 v49, 2, v49
	s_andn2_b64 vcc, exec, s[42:43]
	s_waitcnt lgkmcnt(0)
	v_add_f32_e32 v41, v41, v47
	s_nop 1
	v_mov_b32_dpp v47, v41 row_half_mirror row_mask:0xf bank_mask:0xf
	s_waitcnt lgkmcnt(0)
	v_add_f32_e32 v41, v41, v47
	s_nop 1
	v_mov_b32_dpp v47, v41 row_mirror row_mask:0xf bank_mask:0xf
	s_waitcnt lgkmcnt(0)
	v_add_f32_e32 v41, v41, v47
	ds_bpermute_b32 v47, v49, v41
	s_waitcnt lgkmcnt(0)
	v_add_f32_e32 v41, v41, v47
	v_fmamk_f32 v41, v41, 0x3c800000, v201
	v_mul_f32_e32 v47, 0x4b800000, v41
	v_cmp_gt_f32_e64 s[16:17], s3, v41
	s_nop 1
	v_cndmask_b32_e64 v41, v41, v47, s[16:17]
	v_rsq_f32_e32 v41, v41
	s_nop 0
	v_mul_f32_e32 v47, 0x45800000, v41
	v_cndmask_b32_e64 v41, v41, v47, s[16:17]
	v_mul_f32_e32 v47, v62, v41
	v_mul_f32_e32 v41, v63, v41
	s_mov_b64 s[16:17], -1
	s_waitcnt vmcnt(1)
	v_mul_f32_e32 v39, v39, v47
	s_waitcnt vmcnt(0)
	v_mul_f32_e32 v0, v0, v41
	s_cbranch_vccnz .LBB0_351
	v_bfe_u32 v41, v39, 16, 1
	v_lshlrev_b64 v[74:75], 10, v[64:65]
	v_add3_u32 v41, v39, v41, s2
	v_lshl_add_u64 v[74:75], v[54:55], 0, v[74:75]
	v_ashrrev_i32_e32 v67, 31, v66
	global_store_short_d16_hi v[74:75], v41, off
	v_bfe_u32 v41, v0, 16, 1
	v_lshlrev_b64 v[66:67], 11, v[66:67]
	v_add3_u32 v41, v0, v41, s2
	v_lshl_add_u64 v[66:67], v[52:53], 0, v[66:67]
	s_mov_b64 s[16:17], 0
	global_store_short_d16_hi v[74:75], v41, off offset:64
	global_store_dword v[66:67], v39, off
	global_store_dword v[66:67], v0, off offset:128

; __device__ __forceinline__ unsigned f2bf(float f) { unsigned u = __builtin_bit_cast(unsigned, f); return (u + 0x7fffu + ((u >> 16) & 1u)) >> 16; }
;     __device__ __forceinline__ void operator()(const f32x16& acc0, const f32x16& acc1, int rb, int cg, int r32, int hi, const float (&ss)[16]) const {
;     ...
;             } else if (pn < 10) {
;                 float q = v0 * v0 + v1 * v1;
;                 q += __shfl_xor(q, 1); q += __shfl_xor(q, 2); q += __shfl_xor(q, 4); q += __shfl_xor(q, 8); q += __shfl_xor(q, 16);
;                 const float rn = rsqrtf(q * (1.0f / 64.0f) + EPS);
;                 const bool isq = pn < 8;
;                 const float* gp = isq ? qg : kg;
;                 const int col = ((pn & 1) * 4 + hd) * 64 + r32;
;                 const float a0 = v0 * rn * gp[r32], a1 = v1 * rn * gp[32 + r32];
;                 if (isq) { bf16_t* SQ = (bf16_t*)(ws + WS_SQ); SQ[(size_t)row * 512 + col] = (bf16_t)f2bf(a0 * QSCALE); SQ[(size_t)row * 512 + col + 32] = (bf16_t)f2bf(a1 * QSCALE); }
;                 else { bf16_t* KB = (bf16_t*)(ws + WS_KB); KB[(size_t)row * 512 + col] = (bf16_t)f2bf(a0); KB[(size_t)row * 512 + col + 32] = (bf16_t)f2bf(a1);
;                     Ks[(size_t)rs_ * 512 + col] = a0; Ks[(size_t)rs_ * 512 + col + 32] = a1; }
.LBB0_364:
	s_andn2_b64 vcc, exec, s[16:17]
	s_cbranch_vccnz .LBB0_369
	s_and_b64 s[16:17], s[44:45], exec
	s_cselect_b32 s17, s62, s64
	s_cselect_b32 s16, s61, s63
	v_lshlrev_b32_e32 v0, 2, v98
	global_load_dword v39, v0, s[16:17]
	s_nop 0
	global_load_dword v0, v0, s[16:17] offset:128
	v_pk_mul_f32 v[74:75], v[62:63], v[62:63]
	v_xor_b32_e32 v47, 16, v205
	v_add_f32_e32 v41, v74, v75
	s_nop 1
	v_mov_b32_dpp v43, v41 quad_perm:[1,0,3,2] row_mask:0xf bank_mask:0xf
	v_cmp_lt_i32_e32 vcc, v47, v68
	s_waitcnt lgkmcnt(0)
	v_add_f32_e32 v41, v41, v43
	s_nop 1
	v_mov_b32_dpp v43, v41 quad_perm:[2,3,0,1] row_mask:0xf bank_mask:0xf
	v_cndmask_b32_e32 v47, v205, v47, vcc
	v_lshlrev_b32_e32 v47, 2, v47
	s_andn2_b64 vcc, exec, s[42:43]
	s_waitcnt lgkmcnt(0)
	v_add_f32_e32 v41, v41, v43
	s_nop 1
	v_mov_b32_dpp v43, v41 row_half_mirror row_mask:0xf bank_mask:0xf
	s_waitcnt lgkmcnt(0)
	v_add_f32_e32 v41, v41, v43
	s_nop 1
	v_mov_b32_dpp v43, v41 row_mirror row_mask:0xf bank_mask:0xf
	s_waitcnt lgkmcnt(0)
	v_add_f32_e32 v41, v41, v43
	ds_bpermute_b32 v43, v47, v41
	s_waitcnt lgkmcnt(0)
	v_add_f32_e32 v41, v41, v43
	v_fmamk_f32 v41, v41, 0x3c800000, v201
	v_mul_f32_e32 v43, 0x4b800000, v41
	v_cmp_gt_f32_e64 s[16:17], s3, v41
	s_nop 1
	v_cndmask_b32_e64 v41, v41, v43, s[16:17]
	v_rsq_f32_e32 v41, v41
	s_nop 0
	v_mul_f32_e32 v43, 0x45800000, v41
	v_cndmask_b32_e64 v41, v41, v43, s[16:17]
	v_mul_f32_e32 v43, v62, v41
	v_mul_f32_e32 v41, v63, v41
	s_mov_b64 s[16:17], -1
	s_waitcnt vmcnt(1)
	v_mul_f32_e32 v39, v39, v43
	s_waitcnt vmcnt(0)
	v_mul_f32_e32 v0, v0, v41
	s_cbranch_vccnz .LBB0_367
	v_bfe_u32 v41, v39, 16, 1
	v_lshlrev_b64 v[74:75], 10, v[64:65]
	v_add3_u32 v41, v39, v41, s2
	v_lshl_add_u64 v[74:75], v[54:55], 0, v[74:75]
	v_ashrrev_i32_e32 v67, 31, v66
	global_store_short_d16_hi v[74:75], v41, off
	v_bfe_u32 v41, v0, 16, 1
	v_lshlrev_b64 v[66:67], 11, v[66:67]
	v_add3_u32 v41, v0, v41, s2
	v_lshl_add_u64 v[66:67], v[52:53], 0, v[66:67]
	s_mov_b64 s[16:17], 0
	global_store_short_d16_hi v[74:75], v41, off offset:64
	global_store_dword v[66:67], v39, off
	global_store_dword v[66:67], v0, off offset:128

; __device__ __forceinline__ unsigned f2bf(float f) { unsigned u = __builtin_bit_cast(unsigned, f); return (u + 0x7fffu + ((u >> 16) & 1u)) >> 16; }
;     __device__ __forceinline__ void operator()(const f32x16& acc0, const f32x16& acc1, int rb, int cg, int r32, int hi, const float (&ss)[16]) const {
;     ...
;             } else if (pn < 10) {
;                 float q = v0 * v0 + v1 * v1;
;                 q += __shfl_xor(q, 1); q += __shfl_xor(q, 2); q += __shfl_xor(q, 4); q += __shfl_xor(q, 8); q += __shfl_xor(q, 16);
;                 const float rn = rsqrtf(q * (1.0f / 64.0f) + EPS);
;                 const bool isq = pn < 8;
;                 const float* gp = isq ? qg : kg;
;                 const int col = ((pn & 1) * 4 + hd) * 64 + r32;
;                 const float a0 = v0 * rn * gp[r32], a1 = v1 * rn * gp[32 + r32];
;                 if (isq) { bf16_t* SQ = (bf16_t*)(ws + WS_SQ); SQ[(size_t)row * 512 + col] = (bf16_t)f2bf(a0 * QSCALE); SQ[(size_t)row * 512 + col + 32] = (bf16_t)f2bf(a1 * QSCALE); }
;                 else { bf16_t* KB = (bf16_t*)(ws + WS_KB); KB[(size_t)row * 512 + col] = (bf16_t)f2bf(a0); KB[(size_t)row * 512 + col + 32] = (bf16_t)f2bf(a1);
;                     Ks[(size_t)rs_ * 512 + col] = a0; Ks[(size_t)rs_ * 512 + col + 32] = a1; }
.LBB0_380:
	s_andn2_b64 vcc, exec, s[16:17]
	s_cbranch_vccnz .LBB0_385
	s_and_b64 s[16:17], s[44:45], exec
	s_cselect_b32 s17, s62, s64
	s_cselect_b32 s16, s61, s63
	v_lshlrev_b32_e32 v0, 2, v98
	global_load_dword v39, v0, s[16:17]
	s_nop 0
	global_load_dword v0, v0, s[16:17] offset:128
	v_pk_mul_f32 v[74:75], v[62:63], v[62:63]
	v_xor_b32_e32 v45, 16, v205
	v_add_f32_e32 v41, v74, v75
	s_nop 1
	v_mov_b32_dpp v43, v41 quad_perm:[1,0,3,2] row_mask:0xf bank_mask:0xf
	v_cmp_lt_i32_e32 vcc, v45, v68
	s_waitcnt lgkmcnt(0)
	v_add_f32_e32 v41, v41, v43
	s_nop 1
	v_mov_b32_dpp v43, v41 quad_perm:[2,3,0,1] row_mask:0xf bank_mask:0xf
	v_cndmask_b32_e32 v45, v205, v45, vcc
	v_lshlrev_b32_e32 v45, 2, v45
	s_andn2_b64 vcc, exec, s[42:43]
	s_waitcnt lgkmcnt(0)
	v_add_f32_e32 v41, v41, v43
	s_nop 1
	v_mov_b32_dpp v43, v41 row_half_mirror row_mask:0xf bank_mask:0xf
	s_waitcnt lgkmcnt(0)
	v_add_f32_e32 v41, v41, v43
	s_nop 1
	v_mov_b32_dpp v43, v41 row_mirror row_mask:0xf bank_mask:0xf
	s_waitcnt lgkmcnt(0)
	v_add_f32_e32 v41, v41, v43
	ds_bpermute_b32 v43, v45, v41
	s_waitcnt lgkmcnt(0)
	v_add_f32_e32 v41, v41, v43
	v_fmamk_f32 v41, v41, 0x3c800000, v201
	v_mul_f32_e32 v43, 0x4b800000, v41
	v_cmp_gt_f32_e64 s[16:17], s3, v41
	s_nop 1
	v_cndmask_b32_e64 v41, v41, v43, s[16:17]
	v_rsq_f32_e32 v41, v41
	s_nop 0
	v_mul_f32_e32 v43, 0x45800000, v41
	v_cndmask_b32_e64 v41, v41, v43, s[16:17]
	v_mul_f32_e32 v43, v62, v41
	v_mul_f32_e32 v41, v63, v41
	s_mov_b64 s[16:17], -1
	s_waitcnt vmcnt(1)
	v_mul_f32_e32 v39, v39, v43
	s_waitcnt vmcnt(0)
	v_mul_f32_e32 v0, v0, v41
	s_cbranch_vccnz .LBB0_383
	v_bfe_u32 v41, v39, 16, 1
	v_lshlrev_b64 v[74:75], 10, v[64:65]
	v_add3_u32 v41, v39, v41, s2
	v_lshl_add_u64 v[74:75], v[54:55], 0, v[74:75]
	v_ashrrev_i32_e32 v67, 31, v66
	global_store_short_d16_hi v[74:75], v41, off
	v_bfe_u32 v41, v0, 16, 1
	v_lshlrev_b64 v[66:67], 11, v[66:67]
	v_add3_u32 v41, v0, v41, s2
	v_lshl_add_u64 v[66:67], v[52:53], 0, v[66:67]
	s_mov_b64 s[16:17], 0
	global_store_short_d16_hi v[74:75], v41, off offset:64
	global_store_dword v[66:67], v39, off
	global_store_dword v[66:67], v0, off offset:128

; __device__ __forceinline__ unsigned f2bf(float f) { unsigned u = __builtin_bit_cast(unsigned, f); return (u + 0x7fffu + ((u >> 16) & 1u)) >> 16; }
;     __device__ __forceinline__ void operator()(const f32x16& acc0, const f32x16& acc1, int rb, int cg, int r32, int hi, const float (&ss)[16]) const {
;     ...
;             } else if (pn < 10) {
;                 float q = v0 * v0 + v1 * v1;
;                 q += __shfl_xor(q, 1); q += __shfl_xor(q, 2); q += __shfl_xor(q, 4); q += __shfl_xor(q, 8); q += __shfl_xor(q, 16);
;                 const float rn = rsqrtf(q * (1.0f / 64.0f) + EPS);
;                 const bool isq = pn < 8;
;                 const float* gp = isq ? qg : kg;
;                 const int col = ((pn & 1) * 4 + hd) * 64 + r32;
;                 const float a0 = v0 * rn * gp[r32], a1 = v1 * rn * gp[32 + r32];
;                 if (isq) { bf16_t* SQ = (bf16_t*)(ws + WS_SQ); SQ[(size_t)row * 512 + col] = (bf16_t)f2bf(a0 * QSCALE); SQ[(size_t)row * 512 + col + 32] = (bf16_t)f2bf(a1 * QSCALE); }
;                 else { bf16_t* KB = (bf16_t*)(ws + WS_KB); KB[(size_t)row * 512 + col] = (bf16_t)f2bf(a0); KB[(size_t)row * 512 + col + 32] = (bf16_t)f2bf(a1);
;                     Ks[(size_t)rs_ * 512 + col] = a0; Ks[(size_t)rs_ * 512 + col + 32] = a1; }
.LBB0_396:
	s_andn2_b64 vcc, exec, s[16:17]
	s_cbranch_vccnz .LBB0_401
	s_and_b64 s[16:17], s[44:45], exec
	s_cselect_b32 s17, s62, s64
	s_cselect_b32 s16, s61, s63
	v_lshlrev_b32_e32 v0, 2, v98
	global_load_dword v35, v0, s[16:17]
	s_nop 0
	global_load_dword v0, v0, s[16:17] offset:128
	v_pk_mul_f32 v[74:75], v[62:63], v[62:63]
	v_xor_b32_e32 v43, 16, v205
	v_add_f32_e32 v39, v74, v75
	s_nop 1
	v_mov_b32_dpp v41, v39 quad_perm:[1,0,3,2] row_mask:0xf bank_mask:0xf
	v_cmp_lt_i32_e32 vcc, v43, v68
	s_waitcnt lgkmcnt(0)
	v_add_f32_e32 v39, v39, v41
	s_nop 1
	v_mov_b32_dpp v41, v39 quad_perm:[2,3,0,1] row_mask:0xf bank_mask:0xf
	v_cndmask_b32_e32 v43, v205, v43, vcc
	v_lshlrev_b32_e32 v43, 2, v43
	s_andn2_b64 vcc, exec, s[42:43]
	s_waitcnt lgkmcnt(0)
	v_add_f32_e32 v39, v39, v41
	s_nop 1
	v_mov_b32_dpp v41, v39 row_half_mirror row_mask:0xf bank_mask:0xf
	s_waitcnt lgkmcnt(0)
	v_add_f32_e32 v39, v39, v41
	s_nop 1
	v_mov_b32_dpp v41, v39 row_mirror row_mask:0xf bank_mask:0xf
	s_waitcnt lgkmcnt(0)
	v_add_f32_e32 v39, v39, v41
	ds_bpermute_b32 v41, v43, v39
	s_waitcnt lgkmcnt(0)
	v_add_f32_e32 v39, v39, v41
	v_fmamk_f32 v39, v39, 0x3c800000, v201
	v_mul_f32_e32 v41, 0x4b800000, v39
	v_cmp_gt_f32_e64 s[16:17], s3, v39
	s_nop 1
	v_cndmask_b32_e64 v39, v39, v41, s[16:17]
	v_rsq_f32_e32 v39, v39
	s_nop 0
	v_mul_f32_e32 v41, 0x45800000, v39
	v_cndmask_b32_e64 v39, v39, v41, s[16:17]
	v_mul_f32_e32 v41, v62, v39
	v_mul_f32_e32 v39, v63, v39
	s_mov_b64 s[16:17], -1
	s_waitcnt vmcnt(1)
	v_mul_f32_e32 v35, v35, v41
	s_waitcnt vmcnt(0)
	v_mul_f32_e32 v0, v0, v39
	s_cbranch_vccnz .LBB0_399
	v_bfe_u32 v39, v35, 16, 1
	v_lshlrev_b64 v[74:75], 10, v[64:65]
	v_add3_u32 v39, v35, v39, s2
	v_lshl_add_u64 v[74:75], v[54:55], 0, v[74:75]
	v_ashrrev_i32_e32 v67, 31, v66
	global_store_short_d16_hi v[74:75], v39, off
	v_bfe_u32 v39, v0, 16, 1
	v_lshlrev_b64 v[66:67], 11, v[66:67]
	v_add3_u32 v39, v0, v39, s2
	v_lshl_add_u64 v[66:67], v[52:53], 0, v[66:67]
	s_mov_b64 s[16:17], 0
	global_store_short_d16_hi v[74:75], v39, off offset:64
	global_store_dword v[66:67], v35, off
	global_store_dword v[66:67], v0, off offset:128

; __device__ __forceinline__ unsigned f2bf(float f) { unsigned u = __builtin_bit_cast(unsigned, f); return (u + 0x7fffu + ((u >> 16) & 1u)) >> 16; }
;     __device__ __forceinline__ void operator()(const f32x16& acc0, const f32x16& acc1, int rb, int cg, int r32, int hi, const float (&ss)[16]) const {
;     ...
;             } else if (pn < 10) {
;                 float q = v0 * v0 + v1 * v1;
;                 q += __shfl_xor(q, 1); q += __shfl_xor(q, 2); q += __shfl_xor(q, 4); q += __shfl_xor(q, 8); q += __shfl_xor(q, 16);
;                 const float rn = rsqrtf(q * (1.0f / 64.0f) + EPS);
;                 const bool isq = pn < 8;
;                 const float* gp = isq ? qg : kg;
;                 const int col = ((pn & 1) * 4 + hd) * 64 + r32;
;                 const float a0 = v0 * rn * gp[r32], a1 = v1 * rn * gp[32 + r32];
;                 if (isq) { bf16_t* SQ = (bf16_t*)(ws + WS_SQ); SQ[(size_t)row * 512 + col] = (bf16_t)f2bf(a0 * QSCALE); SQ[(size_t)row * 512 + col + 32] = (bf16_t)f2bf(a1 * QSCALE); }
;                 else { bf16_t* KB = (bf16_t*)(ws + WS_KB); KB[(size_t)row * 512 + col] = (bf16_t)f2bf(a0); KB[(size_t)row * 512 + col + 32] = (bf16_t)f2bf(a1);
;                     Ks[(size_t)rs_ * 512 + col] = a0; Ks[(size_t)rs_ * 512 + col + 32] = a1; }
.LBB0_412:
	s_andn2_b64 vcc, exec, s[16:17]
	s_cbranch_vccnz .LBB0_417
	s_and_b64 s[16:17], s[44:45], exec
	s_cselect_b32 s17, s62, s64
	s_cselect_b32 s16, s61, s63
	v_lshlrev_b32_e32 v0, 2, v98
	global_load_dword v33, v0, s[16:17]
	s_nop 0
	global_load_dword v0, v0, s[16:17] offset:128
	v_pk_mul_f32 v[74:75], v[62:63], v[62:63]
	v_xor_b32_e32 v41, 16, v205
	v_add_f32_e32 v35, v74, v75
	s_nop 1
	v_mov_b32_dpp v39, v35 quad_perm:[1,0,3,2] row_mask:0xf bank_mask:0xf
	v_cmp_lt_i32_e32 vcc, v41, v68
	s_waitcnt lgkmcnt(0)
	v_add_f32_e32 v35, v35, v39
	s_nop 1
	v_mov_b32_dpp v39, v35 quad_perm:[2,3,0,1] row_mask:0xf bank_mask:0xf
	v_cndmask_b32_e32 v41, v205, v41, vcc
	v_lshlrev_b32_e32 v41, 2, v41
	s_andn2_b64 vcc, exec, s[42:43]
	s_waitcnt lgkmcnt(0)
	v_add_f32_e32 v35, v35, v39
	s_nop 1
	v_mov_b32_dpp v39, v35 row_half_mirror row_mask:0xf bank_mask:0xf
	s_waitcnt lgkmcnt(0)
	v_add_f32_e32 v35, v35, v39
	s_nop 1
	v_mov_b32_dpp v39, v35 row_mirror row_mask:0xf bank_mask:0xf
	s_waitcnt lgkmcnt(0)
	v_add_f32_e32 v35, v35, v39
	ds_bpermute_b32 v39, v41, v35
	s_waitcnt lgkmcnt(0)
	v_add_f32_e32 v35, v35, v39
	v_fmamk_f32 v35, v35, 0x3c800000, v201
	v_mul_f32_e32 v39, 0x4b800000, v35
	v_cmp_gt_f32_e64 s[16:17], s3, v35
	s_nop 1
	v_cndmask_b32_e64 v35, v35, v39, s[16:17]
	v_rsq_f32_e32 v35, v35
	s_nop 0
	v_mul_f32_e32 v39, 0x45800000, v35
	v_cndmask_b32_e64 v35, v35, v39, s[16:17]
	v_mul_f32_e32 v39, v62, v35
	v_mul_f32_e32 v35, v63, v35
	s_mov_b64 s[16:17], -1
	s_waitcnt vmcnt(1)
	v_mul_f32_e32 v33, v33, v39
	s_waitcnt vmcnt(0)
	v_mul_f32_e32 v0, v0, v35
	s_cbranch_vccnz .LBB0_415
	v_bfe_u32 v35, v33, 16, 1
	v_lshlrev_b64 v[74:75], 10, v[64:65]
	v_add3_u32 v35, v33, v35, s2
	v_lshl_add_u64 v[74:75], v[54:55], 0, v[74:75]
	v_ashrrev_i32_e32 v67, 31, v66
	global_store_short_d16_hi v[74:75], v35, off
	v_bfe_u32 v35, v0, 16, 1
	v_lshlrev_b64 v[66:67], 11, v[66:67]
	v_add3_u32 v35, v0, v35, s2
	v_lshl_add_u64 v[66:67], v[52:53], 0, v[66:67]
	s_mov_b64 s[16:17], 0
	global_store_short_d16_hi v[74:75], v35, off offset:64
	global_store_dword v[66:67], v33, off
	global_store_dword v[66:67], v0, off offset:128

; __device__ __forceinline__ unsigned f2bf(float f) { unsigned u = __builtin_bit_cast(unsigned, f); return (u + 0x7fffu + ((u >> 16) & 1u)) >> 16; }
;     __device__ __forceinline__ void operator()(const f32x16& acc0, const f32x16& acc1, int rb, int cg, int r32, int hi, const float (&ss)[16]) const {
;     ...
;             } else if (pn < 10) {
;                 float q = v0 * v0 + v1 * v1;
;                 q += __shfl_xor(q, 1); q += __shfl_xor(q, 2); q += __shfl_xor(q, 4); q += __shfl_xor(q, 8); q += __shfl_xor(q, 16);
;                 const float rn = rsqrtf(q * (1.0f / 64.0f) + EPS);
;                 const bool isq = pn < 8;
;                 const float* gp = isq ? qg : kg;
;                 const int col = ((pn & 1) * 4 + hd) * 64 + r32;
;                 const float a0 = v0 * rn * gp[r32], a1 = v1 * rn * gp[32 + r32];
;                 if (isq) { bf16_t* SQ = (bf16_t*)(ws + WS_SQ); SQ[(size_t)row * 512 + col] = (bf16_t)f2bf(a0 * QSCALE); SQ[(size_t)row * 512 + col + 32] = (bf16_t)f2bf(a1 * QSCALE); }
;                 else { bf16_t* KB = (bf16_t*)(ws + WS_KB); KB[(size_t)row * 512 + col] = (bf16_t)f2bf(a0); KB[(size_t)row * 512 + col + 32] = (bf16_t)f2bf(a1);
;                     Ks[(size_t)rs_ * 512 + col] = a0; Ks[(size_t)rs_ * 512 + col + 32] = a1; }
.LBB0_428:
	s_andn2_b64 vcc, exec, s[16:17]
	s_cbranch_vccnz .LBB0_433
	s_and_b64 s[16:17], s[44:45], exec
	s_cselect_b32 s17, s62, s64
	s_cselect_b32 s16, s61, s63
	v_lshlrev_b32_e32 v0, 2, v98
	global_load_dword v27, v0, s[16:17]
	s_nop 0
	global_load_dword v0, v0, s[16:17] offset:128
	v_pk_mul_f32 v[74:75], v[62:63], v[62:63]
	v_xor_b32_e32 v39, 16, v205
	v_add_f32_e32 v33, v74, v75
	s_nop 1
	v_mov_b32_dpp v35, v33 quad_perm:[1,0,3,2] row_mask:0xf bank_mask:0xf
	v_cmp_lt_i32_e32 vcc, v39, v68
	s_waitcnt lgkmcnt(0)
	v_add_f32_e32 v33, v33, v35
	s_nop 1
	v_mov_b32_dpp v35, v33 quad_perm:[2,3,0,1] row_mask:0xf bank_mask:0xf
	v_cndmask_b32_e32 v39, v205, v39, vcc
	v_lshlrev_b32_e32 v39, 2, v39
	s_andn2_b64 vcc, exec, s[42:43]
	s_waitcnt lgkmcnt(0)
	v_add_f32_e32 v33, v33, v35
	s_nop 1
	v_mov_b32_dpp v35, v33 row_half_mirror row_mask:0xf bank_mask:0xf
	s_waitcnt lgkmcnt(0)
	v_add_f32_e32 v33, v33, v35
	s_nop 1
	v_mov_b32_dpp v35, v33 row_mirror row_mask:0xf bank_mask:0xf
	s_waitcnt lgkmcnt(0)
	v_add_f32_e32 v33, v33, v35
	ds_bpermute_b32 v35, v39, v33
	s_waitcnt lgkmcnt(0)
	v_add_f32_e32 v33, v33, v35
	v_fmamk_f32 v33, v33, 0x3c800000, v201
	v_mul_f32_e32 v35, 0x4b800000, v33
	v_cmp_gt_f32_e64 s[16:17], s3, v33
	s_nop 1
	v_cndmask_b32_e64 v33, v33, v35, s[16:17]
	v_rsq_f32_e32 v33, v33
	s_nop 0
	v_mul_f32_e32 v35, 0x45800000, v33
	v_cndmask_b32_e64 v33, v33, v35, s[16:17]
	v_mul_f32_e32 v35, v62, v33
	v_mul_f32_e32 v33, v63, v33
	s_mov_b64 s[16:17], -1
	s_waitcnt vmcnt(1)
	v_mul_f32_e32 v27, v27, v35
	s_waitcnt vmcnt(0)
	v_mul_f32_e32 v0, v0, v33
	s_cbranch_vccnz .LBB0_431
	v_bfe_u32 v33, v27, 16, 1
	v_lshlrev_b64 v[74:75], 10, v[64:65]
	v_add3_u32 v33, v27, v33, s2
	v_lshl_add_u64 v[74:75], v[54:55], 0, v[74:75]
	v_ashrrev_i32_e32 v67, 31, v66
	global_store_short_d16_hi v[74:75], v33, off
	v_bfe_u32 v33, v0, 16, 1
	v_lshlrev_b64 v[66:67], 11, v[66:67]
	v_add3_u32 v33, v0, v33, s2
	v_lshl_add_u64 v[66:67], v[52:53], 0, v[66:67]
	s_mov_b64 s[16:17], 0
	global_store_short_d16_hi v[74:75], v33, off offset:64
	global_store_dword v[66:67], v27, off
	global_store_dword v[66:67], v0, off offset:128

; __device__ __forceinline__ unsigned f2bf(float f) { unsigned u = __builtin_bit_cast(unsigned, f); return (u + 0x7fffu + ((u >> 16) & 1u)) >> 16; }
;     __device__ __forceinline__ void operator()(const f32x16& acc0, const f32x16& acc1, int rb, int cg, int r32, int hi, const float (&ss)[16]) const {
;     ...
;             } else if (pn < 10) {
;                 float q = v0 * v0 + v1 * v1;
;                 q += __shfl_xor(q, 1); q += __shfl_xor(q, 2); q += __shfl_xor(q, 4); q += __shfl_xor(q, 8); q += __shfl_xor(q, 16);
;                 const float rn = rsqrtf(q * (1.0f / 64.0f) + EPS);
;                 const bool isq = pn < 8;
;                 const float* gp = isq ? qg : kg;
;                 const int col = ((pn & 1) * 4 + hd) * 64 + r32;
;                 const float a0 = v0 * rn * gp[r32], a1 = v1 * rn * gp[32 + r32];
;                 if (isq) { bf16_t* SQ = (bf16_t*)(ws + WS_SQ); SQ[(size_t)row * 512 + col] = (bf16_t)f2bf(a0 * QSCALE); SQ[(size_t)row * 512 + col + 32] = (bf16_t)f2bf(a1 * QSCALE); }
;                 else { bf16_t* KB = (bf16_t*)(ws + WS_KB); KB[(size_t)row * 512 + col] = (bf16_t)f2bf(a0); KB[(size_t)row * 512 + col + 32] = (bf16_t)f2bf(a1);
;                     Ks[(size_t)rs_ * 512 + col] = a0; Ks[(size_t)rs_ * 512 + col + 32] = a1; }
.LBB0_444:
	s_andn2_b64 vcc, exec, s[16:17]
	s_cbranch_vccnz .LBB0_449
	s_and_b64 s[16:17], s[44:45], exec
	s_cselect_b32 s17, s62, s64
	s_cselect_b32 s16, s61, s63
	v_lshlrev_b32_e32 v0, 2, v98
	global_load_dword v27, v0, s[16:17]
	s_nop 0
	global_load_dword v0, v0, s[16:17] offset:128
	v_pk_mul_f32 v[74:75], v[62:63], v[62:63]
	v_xor_b32_e32 v35, 16, v205
	v_add_f32_e32 v29, v74, v75
	s_nop 1
	v_mov_b32_dpp v33, v29 quad_perm:[1,0,3,2] row_mask:0xf bank_mask:0xf
	v_cmp_lt_i32_e32 vcc, v35, v68
	s_waitcnt lgkmcnt(0)
	v_add_f32_e32 v29, v29, v33
	s_nop 1
	v_mov_b32_dpp v33, v29 quad_perm:[2,3,0,1] row_mask:0xf bank_mask:0xf
	v_cndmask_b32_e32 v35, v205, v35, vcc
	v_lshlrev_b32_e32 v35, 2, v35
	s_andn2_b64 vcc, exec, s[42:43]
	s_waitcnt lgkmcnt(0)
	v_add_f32_e32 v29, v29, v33
	s_nop 1
	v_mov_b32_dpp v33, v29 row_half_mirror row_mask:0xf bank_mask:0xf
	s_waitcnt lgkmcnt(0)
	v_add_f32_e32 v29, v29, v33
	s_nop 1
	v_mov_b32_dpp v33, v29 row_mirror row_mask:0xf bank_mask:0xf
	s_waitcnt lgkmcnt(0)
	v_add_f32_e32 v29, v29, v33
	ds_bpermute_b32 v33, v35, v29
	s_waitcnt lgkmcnt(0)
	v_add_f32_e32 v29, v29, v33
	v_fmamk_f32 v29, v29, 0x3c800000, v201
	v_mul_f32_e32 v33, 0x4b800000, v29
	v_cmp_gt_f32_e64 s[16:17], s3, v29
	s_nop 1
	v_cndmask_b32_e64 v29, v29, v33, s[16:17]
	v_rsq_f32_e32 v29, v29
	s_nop 0
	v_mul_f32_e32 v33, 0x45800000, v29
	v_cndmask_b32_e64 v29, v29, v33, s[16:17]
	v_mul_f32_e32 v33, v62, v29
	v_mul_f32_e32 v29, v63, v29
	s_mov_b64 s[16:17], -1
	s_waitcnt vmcnt(1)
	v_mul_f32_e32 v27, v27, v33
	s_waitcnt vmcnt(0)
	v_mul_f32_e32 v0, v0, v29
	s_cbranch_vccnz .LBB0_447
	v_bfe_u32 v29, v27, 16, 1
	v_lshlrev_b64 v[74:75], 10, v[64:65]
	v_add3_u32 v29, v27, v29, s2
	v_lshl_add_u64 v[74:75], v[54:55], 0, v[74:75]
	v_ashrrev_i32_e32 v67, 31, v66
	global_store_short_d16_hi v[74:75], v29, off
	v_bfe_u32 v29, v0, 16, 1
	v_lshlrev_b64 v[66:67], 11, v[66:67]
	v_add3_u32 v29, v0, v29, s2
	v_lshl_add_u64 v[66:67], v[52:53], 0, v[66:67]
	s_mov_b64 s[16:17], 0
	global_store_short_d16_hi v[74:75], v29, off offset:64
	global_store_dword v[66:67], v27, off
	global_store_dword v[66:67], v0, off offset:128

; __device__ __forceinline__ unsigned f2bf(float f) { unsigned u = __builtin_bit_cast(unsigned, f); return (u + 0x7fffu + ((u >> 16) & 1u)) >> 16; }
;     __device__ __forceinline__ void operator()(const f32x16& acc0, const f32x16& acc1, int rb, int cg, int r32, int hi, const float (&ss)[16]) const {
;     ...
;             } else if (pn < 10) {
;                 float q = v0 * v0 + v1 * v1;
;                 q += __shfl_xor(q, 1); q += __shfl_xor(q, 2); q += __shfl_xor(q, 4); q += __shfl_xor(q, 8); q += __shfl_xor(q, 16);
;                 const float rn = rsqrtf(q * (1.0f / 64.0f) + EPS);
;                 const bool isq = pn < 8;
;                 const float* gp = isq ? qg : kg;
;                 const int col = ((pn & 1) * 4 + hd) * 64 + r32;
;                 const float a0 = v0 * rn * gp[r32], a1 = v1 * rn * gp[32 + r32];
;                 if (isq) { bf16_t* SQ = (bf16_t*)(ws + WS_SQ); SQ[(size_t)row * 512 + col] = (bf16_t)f2bf(a0 * QSCALE); SQ[(size_t)row * 512 + col + 32] = (bf16_t)f2bf(a1 * QSCALE); }
;                 else { bf16_t* KB = (bf16_t*)(ws + WS_KB); KB[(size_t)row * 512 + col] = (bf16_t)f2bf(a0); KB[(size_t)row * 512 + col + 32] = (bf16_t)f2bf(a1);
;                     Ks[(size_t)rs_ * 512 + col] = a0; Ks[(size_t)rs_ * 512 + col + 32] = a1; }
.LBB0_460:
	s_andn2_b64 vcc, exec, s[16:17]
	s_cbranch_vccnz .LBB0_465
	s_and_b64 s[16:17], s[44:45], exec
	s_cselect_b32 s17, s62, s64
	s_cselect_b32 s16, s61, s63
	v_lshlrev_b32_e32 v0, 2, v98
	global_load_dword v23, v0, s[16:17]
	s_nop 0
	global_load_dword v0, v0, s[16:17] offset:128
	v_pk_mul_f32 v[74:75], v[62:63], v[62:63]
	v_xor_b32_e32 v33, 16, v205
	v_add_f32_e32 v27, v74, v75
	s_nop 1
	v_mov_b32_dpp v29, v27 quad_perm:[1,0,3,2] row_mask:0xf bank_mask:0xf
	v_cmp_lt_i32_e32 vcc, v33, v68
	s_waitcnt lgkmcnt(0)
	v_add_f32_e32 v27, v27, v29
	s_nop 1
	v_mov_b32_dpp v29, v27 quad_perm:[2,3,0,1] row_mask:0xf bank_mask:0xf
	v_cndmask_b32_e32 v33, v205, v33, vcc
	v_lshlrev_b32_e32 v33, 2, v33
	s_andn2_b64 vcc, exec, s[42:43]
	s_waitcnt lgkmcnt(0)
	v_add_f32_e32 v27, v27, v29
	s_nop 1
	v_mov_b32_dpp v29, v27 row_half_mirror row_mask:0xf bank_mask:0xf
	s_waitcnt lgkmcnt(0)
	v_add_f32_e32 v27, v27, v29
	s_nop 1
	v_mov_b32_dpp v29, v27 row_mirror row_mask:0xf bank_mask:0xf
	s_waitcnt lgkmcnt(0)
	v_add_f32_e32 v27, v27, v29
	ds_bpermute_b32 v29, v33, v27
	s_waitcnt lgkmcnt(0)
	v_add_f32_e32 v27, v27, v29
	v_fmamk_f32 v27, v27, 0x3c800000, v201
	v_mul_f32_e32 v29, 0x4b800000, v27
	v_cmp_gt_f32_e64 s[16:17], s3, v27
	s_nop 1
	v_cndmask_b32_e64 v27, v27, v29, s[16:17]
	v_rsq_f32_e32 v27, v27
	s_nop 0
	v_mul_f32_e32 v29, 0x45800000, v27
	v_cndmask_b32_e64 v27, v27, v29, s[16:17]
	v_mul_f32_e32 v29, v62, v27
	v_mul_f32_e32 v27, v63, v27
	s_mov_b64 s[16:17], -1
	s_waitcnt vmcnt(1)
	v_mul_f32_e32 v23, v23, v29
	s_waitcnt vmcnt(0)
	v_mul_f32_e32 v0, v0, v27
	s_cbranch_vccnz .LBB0_463
	v_bfe_u32 v27, v23, 16, 1
	v_lshlrev_b64 v[74:75], 10, v[64:65]
	v_add3_u32 v27, v23, v27, s2
	v_lshl_add_u64 v[74:75], v[54:55], 0, v[74:75]
	v_ashrrev_i32_e32 v67, 31, v66
	global_store_short_d16_hi v[74:75], v27, off
	v_bfe_u32 v27, v0, 16, 1
	v_lshlrev_b64 v[66:67], 11, v[66:67]
	v_add3_u32 v27, v0, v27, s2
	v_lshl_add_u64 v[66:67], v[52:53], 0, v[66:67]
	s_mov_b64 s[16:17], 0
	global_store_short_d16_hi v[74:75], v27, off offset:64
	global_store_dword v[66:67], v23, off
	global_store_dword v[66:67], v0, off offset:128

; __device__ __forceinline__ unsigned f2bf(float f) { unsigned u = __builtin_bit_cast(unsigned, f); return (u + 0x7fffu + ((u >> 16) & 1u)) >> 16; }
;     __device__ __forceinline__ void operator()(const f32x16& acc0, const f32x16& acc1, int rb, int cg, int r32, int hi, const float (&ss)[16]) const {
;     ...
;             } else if (pn < 10) {
;                 float q = v0 * v0 + v1 * v1;
;                 q += __shfl_xor(q, 1); q += __shfl_xor(q, 2); q += __shfl_xor(q, 4); q += __shfl_xor(q, 8); q += __shfl_xor(q, 16);
;                 const float rn = rsqrtf(q * (1.0f / 64.0f) + EPS);
;                 const bool isq = pn < 8;
;                 const float* gp = isq ? qg : kg;
;                 const int col = ((pn & 1) * 4 + hd) * 64 + r32;
;                 const float a0 = v0 * rn * gp[r32], a1 = v1 * rn * gp[32 + r32];
;                 if (isq) { bf16_t* SQ = (bf16_t*)(ws + WS_SQ); SQ[(size_t)row * 512 + col] = (bf16_t)f2bf(a0 * QSCALE); SQ[(size_t)row * 512 + col + 32] = (bf16_t)f2bf(a1 * QSCALE); }
;                 else { bf16_t* KB = (bf16_t*)(ws + WS_KB); KB[(size_t)row * 512 + col] = (bf16_t)f2bf(a0); KB[(size_t)row * 512 + col + 32] = (bf16_t)f2bf(a1);
;                     Ks[(size_t)rs_ * 512 + col] = a0; Ks[(size_t)rs_ * 512 + col + 32] = a1; }
.LBB0_476:
	s_andn2_b64 vcc, exec, s[16:17]
	s_cbranch_vccnz .LBB0_481
	s_and_b64 s[16:17], s[44:45], exec
	s_cselect_b32 s17, s62, s64
	s_cselect_b32 s16, s61, s63
	v_lshlrev_b32_e32 v0, 2, v98
	global_load_dword v21, v0, s[16:17]
	s_nop 0
	global_load_dword v0, v0, s[16:17] offset:128
	v_pk_mul_f32 v[74:75], v[62:63], v[62:63]
	v_xor_b32_e32 v29, 16, v205
	v_add_f32_e32 v23, v74, v75
	s_nop 1
	v_mov_b32_dpp v27, v23 quad_perm:[1,0,3,2] row_mask:0xf bank_mask:0xf
	v_cmp_lt_i32_e32 vcc, v29, v68
	s_waitcnt lgkmcnt(0)
	v_add_f32_e32 v23, v23, v27
	s_nop 1
	v_mov_b32_dpp v27, v23 quad_perm:[2,3,0,1] row_mask:0xf bank_mask:0xf
	v_cndmask_b32_e32 v29, v205, v29, vcc
	v_lshlrev_b32_e32 v29, 2, v29
	s_andn2_b64 vcc, exec, s[42:43]
	s_waitcnt lgkmcnt(0)
	v_add_f32_e32 v23, v23, v27
	s_nop 1
	v_mov_b32_dpp v27, v23 row_half_mirror row_mask:0xf bank_mask:0xf
	s_waitcnt lgkmcnt(0)
	v_add_f32_e32 v23, v23, v27
	s_nop 1
	v_mov_b32_dpp v27, v23 row_mirror row_mask:0xf bank_mask:0xf
	s_waitcnt lgkmcnt(0)
	v_add_f32_e32 v23, v23, v27
	ds_bpermute_b32 v27, v29, v23
	s_waitcnt lgkmcnt(0)
	v_add_f32_e32 v23, v23, v27
	v_fmamk_f32 v23, v23, 0x3c800000, v201
	v_mul_f32_e32 v27, 0x4b800000, v23
	v_cmp_gt_f32_e64 s[16:17], s3, v23
	s_nop 1
	v_cndmask_b32_e64 v23, v23, v27, s[16:17]
	v_rsq_f32_e32 v23, v23
	s_nop 0
	v_mul_f32_e32 v27, 0x45800000, v23
	v_cndmask_b32_e64 v23, v23, v27, s[16:17]
	v_mul_f32_e32 v27, v62, v23
	v_mul_f32_e32 v23, v63, v23
	s_mov_b64 s[16:17], -1
	s_waitcnt vmcnt(1)
	v_mul_f32_e32 v21, v21, v27
	s_waitcnt vmcnt(0)
	v_mul_f32_e32 v0, v0, v23
	s_cbranch_vccnz .LBB0_479
	v_bfe_u32 v23, v21, 16, 1
	v_lshlrev_b64 v[74:75], 10, v[64:65]
	v_add3_u32 v23, v21, v23, s2
	v_lshl_add_u64 v[74:75], v[54:55], 0, v[74:75]
	v_ashrrev_i32_e32 v67, 31, v66
	global_store_short_d16_hi v[74:75], v23, off
	v_bfe_u32 v23, v0, 16, 1
	v_lshlrev_b64 v[66:67], 11, v[66:67]
	v_add3_u32 v23, v0, v23, s2
	v_lshl_add_u64 v[66:67], v[52:53], 0, v[66:67]
	s_mov_b64 s[16:17], 0
	global_store_short_d16_hi v[74:75], v23, off offset:64
	global_store_dword v[66:67], v21, off
	global_store_dword v[66:67], v0, off offset:128

; __device__ __forceinline__ unsigned f2bf(float f) { unsigned u = __builtin_bit_cast(unsigned, f); return (u + 0x7fffu + ((u >> 16) & 1u)) >> 16; }
;     __device__ __forceinline__ void operator()(const f32x16& acc0, const f32x16& acc1, int rb, int cg, int r32, int hi, const float (&ss)[16]) const {
;     ...
;             } else if (pn < 10) {
;                 float q = v0 * v0 + v1 * v1;
;                 q += __shfl_xor(q, 1); q += __shfl_xor(q, 2); q += __shfl_xor(q, 4); q += __shfl_xor(q, 8); q += __shfl_xor(q, 16);
;                 const float rn = rsqrtf(q * (1.0f / 64.0f) + EPS);
;                 const bool isq = pn < 8;
;                 const float* gp = isq ? qg : kg;
;                 const int col = ((pn & 1) * 4 + hd) * 64 + r32;
;                 const float a0 = v0 * rn * gp[r32], a1 = v1 * rn * gp[32 + r32];
;                 if (isq) { bf16_t* SQ = (bf16_t*)(ws + WS_SQ); SQ[(size_t)row * 512 + col] = (bf16_t)f2bf(a0 * QSCALE); SQ[(size_t)row * 512 + col + 32] = (bf16_t)f2bf(a1 * QSCALE); }
;                 else { bf16_t* KB = (bf16_t*)(ws + WS_KB); KB[(size_t)row * 512 + col] = (bf16_t)f2bf(a0); KB[(size_t)row * 512 + col + 32] = (bf16_t)f2bf(a1);
;                     Ks[(size_t)rs_ * 512 + col] = a0; Ks[(size_t)rs_ * 512 + col + 32] = a1; }
.LBB0_524:
	s_andn2_b64 vcc, exec, s[14:15]
	s_cbranch_vccnz .LBB0_529
	s_and_b64 s[12:13], s[44:45], exec
	s_cselect_b32 s13, s62, s64
	s_cselect_b32 s12, s61, s63
	v_lshlrev_b32_e32 v0, 2, v98
	global_load_dword v21, v0, s[12:13]
	s_nop 0
	global_load_dword v0, v0, s[12:13] offset:128
	v_pk_mul_f32 v[56:57], v[62:63], v[62:63]
	v_xor_b32_e32 v27, 16, v205
	v_add_f32_e32 v23, v56, v57
	s_nop 1
	v_mov_b32_dpp v25, v23 quad_perm:[1,0,3,2] row_mask:0xf bank_mask:0xf
	v_cmp_lt_i32_e32 vcc, v27, v68
	s_waitcnt lgkmcnt(0)
	v_add_f32_e32 v23, v23, v25
	s_nop 1
	v_mov_b32_dpp v25, v23 quad_perm:[2,3,0,1] row_mask:0xf bank_mask:0xf
	v_cndmask_b32_e32 v27, v205, v27, vcc
	v_lshlrev_b32_e32 v27, 2, v27
	s_andn2_b64 vcc, exec, s[42:43]
	s_waitcnt lgkmcnt(0)
	v_add_f32_e32 v23, v23, v25
	s_nop 1
	v_mov_b32_dpp v25, v23 row_half_mirror row_mask:0xf bank_mask:0xf
	s_waitcnt lgkmcnt(0)
	v_add_f32_e32 v23, v23, v25
	s_nop 1
	v_mov_b32_dpp v25, v23 row_mirror row_mask:0xf bank_mask:0xf
	s_waitcnt lgkmcnt(0)
	v_add_f32_e32 v23, v23, v25
	ds_bpermute_b32 v25, v27, v23
	s_waitcnt lgkmcnt(0)
	v_add_f32_e32 v23, v23, v25
	v_fmamk_f32 v23, v23, 0x3c800000, v201
	v_mul_f32_e32 v25, 0x4b800000, v23
	v_cmp_gt_f32_e64 s[12:13], s3, v23
	s_nop 1
	v_cndmask_b32_e64 v23, v23, v25, s[12:13]
	v_rsq_f32_e32 v23, v23
	s_nop 0
	v_mul_f32_e32 v25, 0x45800000, v23
	v_cndmask_b32_e64 v23, v23, v25, s[12:13]
	v_mul_f32_e32 v25, v62, v23
	v_mul_f32_e32 v23, v63, v23
	s_mov_b64 s[12:13], -1
	s_waitcnt vmcnt(1)
	v_mul_f32_e32 v21, v21, v25
	s_waitcnt vmcnt(0)
	v_mul_f32_e32 v0, v0, v23
	s_cbranch_vccnz .LBB0_527
	v_bfe_u32 v23, v21, 16, 1
	v_lshlrev_b64 v[56:57], 10, v[64:65]
	v_add3_u32 v23, v21, v23, s2
	v_lshl_add_u64 v[54:55], v[54:55], 0, v[56:57]
	global_store_short_d16_hi v[54:55], v23, off
	v_bfe_u32 v23, v0, 16, 1
	v_add3_u32 v23, v0, v23, s2
	v_ashrrev_i32_e32 v61, 31, v60
	global_store_short_d16_hi v[54:55], v23, off offset:64
	v_lshlrev_b64 v[54:55], 11, v[60:61]
	v_lshl_add_u64 v[52:53], v[52:53], 0, v[54:55]
	s_mov_b64 s[12:13], 0
	global_store_dword v[52:53], v21, off
	global_store_dword v[52:53], v0, off offset:128
